# attention fast path: packed f32 row-sum adds inside the PV MFMA gaps split into single v_add_f32 (packed VOP3P between MFMAs stalls issue); scan recurrence waves at prio 3
# baseline (speedup 1.0000x reference)
.LaF1_2:
	v_sub_f32_e32 v66, v66, v183
	v_sub_f32_e32 v67, v67, v183
	v_sub_f32_e32 v68, v68, v183
	v_sub_f32_e32 v69, v69, v183
	v_sub_f32_e32 v70, v70, v183
	v_sub_f32_e32 v71, v71, v183
	v_sub_f32_e32 v72, v72, v183
	v_sub_f32_e32 v73, v73, v183
	v_sub_f32_e32 v74, v74, v183
	v_sub_f32_e32 v75, v75, v183
	v_sub_f32_e32 v76, v76, v183
	v_sub_f32_e32 v77, v77, v183
	v_sub_f32_e32 v78, v78, v183
	v_sub_f32_e32 v79, v79, v183
	v_sub_f32_e32 v80, v80, v183
	v_sub_f32_e32 v81, v81, v183
	v_exp_f32_e32 v66, v66
	v_exp_f32_e32 v67, v67
	v_exp_f32_e32 v68, v68
	v_exp_f32_e32 v69, v69
	v_exp_f32_e32 v70, v70
	v_exp_f32_e32 v71, v71
	v_exp_f32_e32 v72, v72
	v_exp_f32_e32 v73, v73
	v_exp_f32_e32 v74, v74
	v_exp_f32_e32 v75, v75
	v_exp_f32_e32 v76, v76
	v_exp_f32_e32 v77, v77
	v_exp_f32_e32 v78, v78
	v_exp_f32_e32 v79, v79
	v_exp_f32_e32 v80, v80
	v_exp_f32_e32 v81, v81
	v_pk_add_f32 v[184:185], v[66:67], v[68:69]
	v_pk_add_f32 v[186:187], v[70:71], v[72:73]
	v_pk_add_f32 v[184:185], v[184:185], v[74:75]
	v_pk_add_f32 v[186:187], v[186:187], v[76:77]
	v_pk_add_f32 v[184:185], v[184:185], v[78:79]
	v_pk_add_f32 v[186:187], v[186:187], v[80:81]
	v_cvt_pk_bf16_f32 v66, v66, v67
	v_cvt_pk_bf16_f32 v67, v68, v69
	v_cvt_pk_bf16_f32 v68, v70, v71
	v_cvt_pk_bf16_f32 v69, v72, v73
	v_cvt_pk_bf16_f32 v70, v74, v75
	v_cvt_pk_bf16_f32 v71, v76, v77
	v_cvt_pk_bf16_f32 v72, v78, v79
	v_cvt_pk_bf16_f32 v73, v80, v81
	s_nop 1
	s_setprio 1
	s_waitcnt lgkmcnt(5)
	v_mfma_f32_32x32x16_bf16 v[50:65], v[196:199], v[66:69], v[50:65]
	ds_read_b128 v[220:223], v252 offset:34848
	v_sub_f32_e32 v82, v82, v183
	v_sub_f32_e32 v83, v83, v183
	v_sub_f32_e32 v84, v84, v183
	v_sub_f32_e32 v85, v85, v183
	v_sub_f32_e32 v86, v86, v183
	v_sub_f32_e32 v87, v87, v183
	v_sub_f32_e32 v88, v88, v183
	v_sub_f32_e32 v89, v89, v183
	s_waitcnt lgkmcnt(5)
	v_mfma_f32_32x32x16_bf16 v[34:49], v[200:203], v[66:69], v[34:49]
	ds_read_b128 v[224:227], v252 offset:39456
	v_sub_f32_e32 v90, v90, v183
	v_sub_f32_e32 v91, v91, v183
	v_sub_f32_e32 v92, v92, v183
	v_sub_f32_e32 v93, v93, v183
	v_sub_f32_e32 v94, v94, v183
	v_sub_f32_e32 v95, v95, v183
	v_sub_f32_e32 v96, v96, v183
	v_sub_f32_e32 v97, v97, v183
	s_waitcnt lgkmcnt(5)
	v_mfma_f32_32x32x16_bf16 v[18:33], v[204:207], v[66:69], v[18:33]
	ds_read_b128 v[228:231], v252 offset:25664
	v_exp_f32_e32 v82, v82
	v_exp_f32_e32 v83, v83
	v_exp_f32_e32 v84, v84
	v_exp_f32_e32 v85, v85
	v_exp_f32_e32 v86, v86
	v_exp_f32_e32 v87, v87
	v_exp_f32_e32 v88, v88
	v_exp_f32_e32 v89, v89
	s_waitcnt lgkmcnt(5)
	v_mfma_f32_32x32x16_bf16 v[2:17], v[208:211], v[66:69], v[2:17]
	ds_read_b128 v[232:235], v252 offset:30272
	v_exp_f32_e32 v90, v90
	v_exp_f32_e32 v91, v91
	v_exp_f32_e32 v92, v92
	v_exp_f32_e32 v93, v93
	v_exp_f32_e32 v94, v94
	v_exp_f32_e32 v95, v95
	v_exp_f32_e32 v96, v96
	v_exp_f32_e32 v97, v97
	s_waitcnt lgkmcnt(5)
	v_mfma_f32_32x32x16_bf16 v[50:65], v[212:215], v[70:73], v[50:65]
	ds_read_b128 v[236:239], v252 offset:34880
	v_add_f32_e32 v184, v184, v82
	v_add_f32_e32 v185, v185, v83
	v_add_f32_e32 v186, v186, v84
	v_add_f32_e32 v187, v187, v85
	v_add_f32_e32 v184, v184, v86
	v_add_f32_e32 v185, v185, v87
	v_add_f32_e32 v186, v186, v88
	v_add_f32_e32 v187, v187, v89
	s_waitcnt lgkmcnt(5)
	v_mfma_f32_32x32x16_bf16 v[34:49], v[216:219], v[70:73], v[34:49]
	ds_read_b128 v[240:243], v252 offset:39488
	v_add_f32_e32 v184, v184, v90
	v_add_f32_e32 v185, v185, v91
	v_add_f32_e32 v186, v186, v92
	v_add_f32_e32 v187, v187, v93
	v_add_f32_e32 v184, v184, v94
	v_add_f32_e32 v185, v185, v95
	v_add_f32_e32 v186, v186, v96
	v_add_f32_e32 v187, v187, v97
	s_waitcnt lgkmcnt(5)
	v_mfma_f32_32x32x16_bf16 v[18:33], v[220:223], v[70:73], v[18:33]
	ds_read_b128 v[196:199], v252 offset:25696
	v_add_f32_e32 v184, v184, v186
	v_add_f32_e32 v185, v185, v187
	v_cvt_pk_bf16_f32 v74, v82, v83
	v_cvt_pk_bf16_f32 v75, v84, v85
	v_cvt_pk_bf16_f32 v76, v86, v87
	v_cvt_pk_bf16_f32 v77, v88, v89
	v_cvt_pk_bf16_f32 v78, v90, v91
	v_cvt_pk_bf16_f32 v79, v92, v93
	s_waitcnt lgkmcnt(5)
	v_mfma_f32_32x32x16_bf16 v[2:17], v[224:227], v[70:73], v[2:17]
	ds_read_b128 v[200:203], v252 offset:30304
	v_cvt_pk_bf16_f32 v80, v94, v95
	v_cvt_pk_bf16_f32 v81, v96, v97
	v_add_f32_e32 v184, v184, v185
	v_add_f32_e32 v182, v182, v184
	s_waitcnt lgkmcnt(5)
	v_mfma_f32_32x32x16_bf16 v[50:65], v[228:231], v[74:77], v[50:65]
	ds_read_b128 v[204:207], v252 offset:34912
	s_bitcmp1_b32 s51, 0
	s_cselect_b32 s99, 0xac00, 0
	s_waitcnt lgkmcnt(5)
	v_mfma_f32_32x32x16_bf16 v[34:49], v[232:235], v[74:77], v[34:49]
	ds_read_b128 v[208:211], v252 offset:39520
	s_add_i32 s99, s99, 0
	v_add_u32_e32 v250, s99, v170
	s_waitcnt lgkmcnt(5)
	v_mfma_f32_32x32x16_bf16 v[18:33], v[236:239], v[74:77], v[18:33]
	s_waitcnt vmcnt(4)
	ds_write_b128 v250, v[98:101]
	s_waitcnt lgkmcnt(5)
	v_mfma_f32_32x32x16_bf16 v[2:17], v[240:243], v[74:77], v[2:17]
	s_waitcnt vmcnt(3)
	ds_write_b128 v250, v[102:105] offset:12800
	s_waitcnt lgkmcnt(5)
	v_mfma_f32_32x32x16_bf16 v[50:65], v[196:199], v[78:81], v[50:65]
	v_add_u32_e32 v250, s99, v172
	s_waitcnt vmcnt(2)
	s_waitcnt lgkmcnt(4)
	v_mfma_f32_32x32x16_bf16 v[34:49], v[200:203], v[78:81], v[34:49]
	ds_write_b128 v250, v[106:109] offset:256
	v_add_u32_e32 v250, s99, v169
	s_waitcnt lgkmcnt(4)
	v_mfma_f32_32x32x16_bf16 v[18:33], v[204:207], v[78:81], v[18:33]
	s_waitcnt vmcnt(1)
	ds_write_b128 v250, v[114:117] offset:25600
	s_waitcnt lgkmcnt(4)
	v_mfma_f32_32x32x16_bf16 v[2:17], v[208:211], v[78:81], v[2:17]
	s_waitcnt vmcnt(0)
	ds_write_b128 v250, v[146:149] offset:34816
	s_setprio 0
	s_branch .LBB0_1478

.LaF2_2:
	v_sub_f32_e32 v66, v66, v183
	v_sub_f32_e32 v67, v67, v183
	v_sub_f32_e32 v68, v68, v183
	v_sub_f32_e32 v69, v69, v183
	v_sub_f32_e32 v70, v70, v183
	v_sub_f32_e32 v71, v71, v183
	v_sub_f32_e32 v72, v72, v183
	v_sub_f32_e32 v73, v73, v183
	v_sub_f32_e32 v74, v74, v183
	v_sub_f32_e32 v75, v75, v183
	v_sub_f32_e32 v76, v76, v183
	v_sub_f32_e32 v77, v77, v183
	v_sub_f32_e32 v78, v78, v183
	v_sub_f32_e32 v79, v79, v183
	v_sub_f32_e32 v80, v80, v183
	v_sub_f32_e32 v81, v81, v183
	v_exp_f32_e32 v66, v66
	v_exp_f32_e32 v67, v67
	v_exp_f32_e32 v68, v68
	v_exp_f32_e32 v69, v69
	v_exp_f32_e32 v70, v70
	v_exp_f32_e32 v71, v71
	v_exp_f32_e32 v72, v72
	v_exp_f32_e32 v73, v73
	v_exp_f32_e32 v74, v74
	v_exp_f32_e32 v75, v75
	v_exp_f32_e32 v76, v76
	v_exp_f32_e32 v77, v77
	v_exp_f32_e32 v78, v78
	v_exp_f32_e32 v79, v79
	v_exp_f32_e32 v80, v80
	v_exp_f32_e32 v81, v81
	v_pk_add_f32 v[184:185], v[66:67], v[68:69]
	v_pk_add_f32 v[186:187], v[70:71], v[72:73]
	v_pk_add_f32 v[184:185], v[184:185], v[74:75]
	v_pk_add_f32 v[186:187], v[186:187], v[76:77]
	v_pk_add_f32 v[184:185], v[184:185], v[78:79]
	v_pk_add_f32 v[186:187], v[186:187], v[80:81]
	v_cvt_pk_bf16_f32 v66, v66, v67
	v_cvt_pk_bf16_f32 v67, v68, v69
	v_cvt_pk_bf16_f32 v68, v70, v71
	v_cvt_pk_bf16_f32 v69, v72, v73
	v_cvt_pk_bf16_f32 v70, v74, v75
	v_cvt_pk_bf16_f32 v71, v76, v77
	v_cvt_pk_bf16_f32 v72, v78, v79
	v_cvt_pk_bf16_f32 v73, v80, v81
	s_nop 1
	s_setprio 1
	s_waitcnt lgkmcnt(5)
	v_mfma_f32_32x32x16_bf16 v[50:65], v[196:199], v[66:69], v[50:65]
	ds_read_b128 v[220:223], v252 offset:34848
	v_sub_f32_e32 v82, v82, v183
	v_sub_f32_e32 v83, v83, v183
	v_sub_f32_e32 v84, v84, v183
	v_sub_f32_e32 v85, v85, v183
	v_sub_f32_e32 v86, v86, v183
	v_sub_f32_e32 v87, v87, v183
	v_sub_f32_e32 v88, v88, v183
	v_sub_f32_e32 v89, v89, v183
	s_waitcnt lgkmcnt(5)
	v_mfma_f32_32x32x16_bf16 v[34:49], v[200:203], v[66:69], v[34:49]
	ds_read_b128 v[224:227], v252 offset:39456
	v_sub_f32_e32 v90, v90, v183
	v_sub_f32_e32 v91, v91, v183
	v_sub_f32_e32 v92, v92, v183
	v_sub_f32_e32 v93, v93, v183
	v_sub_f32_e32 v94, v94, v183
	v_sub_f32_e32 v95, v95, v183
	v_sub_f32_e32 v96, v96, v183
	v_sub_f32_e32 v97, v97, v183
	s_waitcnt lgkmcnt(5)
	v_mfma_f32_32x32x16_bf16 v[18:33], v[204:207], v[66:69], v[18:33]
	ds_read_b128 v[228:231], v252 offset:25664
	v_exp_f32_e32 v82, v82
	v_exp_f32_e32 v83, v83
	v_exp_f32_e32 v84, v84
	v_exp_f32_e32 v85, v85
	v_exp_f32_e32 v86, v86
	v_exp_f32_e32 v87, v87
	v_exp_f32_e32 v88, v88
	v_exp_f32_e32 v89, v89
	s_waitcnt lgkmcnt(5)
	v_mfma_f32_32x32x16_bf16 v[2:17], v[208:211], v[66:69], v[2:17]
	ds_read_b128 v[232:235], v252 offset:30272
	v_exp_f32_e32 v90, v90
	v_exp_f32_e32 v91, v91
	v_exp_f32_e32 v92, v92
	v_exp_f32_e32 v93, v93
	v_exp_f32_e32 v94, v94
	v_exp_f32_e32 v95, v95
	v_exp_f32_e32 v96, v96
	v_exp_f32_e32 v97, v97
	s_waitcnt lgkmcnt(5)
	v_mfma_f32_32x32x16_bf16 v[50:65], v[212:215], v[70:73], v[50:65]
	ds_read_b128 v[236:239], v252 offset:34880
	v_add_f32_e32 v184, v184, v82
	v_add_f32_e32 v185, v185, v83
	v_add_f32_e32 v186, v186, v84
	v_add_f32_e32 v187, v187, v85
	v_add_f32_e32 v184, v184, v86
	v_add_f32_e32 v185, v185, v87
	v_add_f32_e32 v186, v186, v88
	v_add_f32_e32 v187, v187, v89
	s_waitcnt lgkmcnt(5)
	v_mfma_f32_32x32x16_bf16 v[34:49], v[216:219], v[70:73], v[34:49]
	ds_read_b128 v[240:243], v252 offset:39488
	v_add_f32_e32 v184, v184, v90
	v_add_f32_e32 v185, v185, v91
	v_add_f32_e32 v186, v186, v92
	v_add_f32_e32 v187, v187, v93
	v_add_f32_e32 v184, v184, v94
	v_add_f32_e32 v185, v185, v95
	v_add_f32_e32 v186, v186, v96
	v_add_f32_e32 v187, v187, v97
	s_waitcnt lgkmcnt(5)
	v_mfma_f32_32x32x16_bf16 v[18:33], v[220:223], v[70:73], v[18:33]
	ds_read_b128 v[196:199], v252 offset:25696
	v_add_f32_e32 v184, v184, v186
	v_add_f32_e32 v185, v185, v187
	v_cvt_pk_bf16_f32 v74, v82, v83
	v_cvt_pk_bf16_f32 v75, v84, v85
	v_cvt_pk_bf16_f32 v76, v86, v87
	v_cvt_pk_bf16_f32 v77, v88, v89
	v_cvt_pk_bf16_f32 v78, v90, v91
	v_cvt_pk_bf16_f32 v79, v92, v93
	s_waitcnt lgkmcnt(5)
	v_mfma_f32_32x32x16_bf16 v[2:17], v[224:227], v[70:73], v[2:17]
	ds_read_b128 v[200:203], v252 offset:30304
	v_cvt_pk_bf16_f32 v80, v94, v95
	v_cvt_pk_bf16_f32 v81, v96, v97
	v_add_f32_e32 v184, v184, v185
	v_add_f32_e32 v182, v182, v184
	s_waitcnt lgkmcnt(5)
	v_mfma_f32_32x32x16_bf16 v[50:65], v[228:231], v[74:77], v[50:65]
	ds_read_b128 v[204:207], v252 offset:34912
	s_bitcmp1_b32 s36, 0
	s_cselect_b32 s99, 0xac00, 0
	s_waitcnt lgkmcnt(5)
	v_mfma_f32_32x32x16_bf16 v[34:49], v[232:235], v[74:77], v[34:49]
	ds_read_b128 v[208:211], v252 offset:39520
	s_add_i32 s99, s99, 0
	v_add_u32_e32 v250, s99, v170
	s_waitcnt lgkmcnt(5)
	v_mfma_f32_32x32x16_bf16 v[18:33], v[236:239], v[74:77], v[18:33]
	s_waitcnt vmcnt(4)
	ds_write_b128 v250, v[98:101]
	s_waitcnt lgkmcnt(5)
	v_mfma_f32_32x32x16_bf16 v[2:17], v[240:243], v[74:77], v[2:17]
	s_waitcnt vmcnt(3)
	ds_write_b128 v250, v[102:105] offset:12800
	s_waitcnt lgkmcnt(5)
	v_mfma_f32_32x32x16_bf16 v[50:65], v[196:199], v[78:81], v[50:65]
	v_add_u32_e32 v250, s99, v172
	s_waitcnt vmcnt(2)
	s_waitcnt lgkmcnt(4)
	v_mfma_f32_32x32x16_bf16 v[34:49], v[200:203], v[78:81], v[34:49]
	ds_write_b128 v250, v[106:109] offset:256
	v_add_u32_e32 v250, s99, v169
	s_waitcnt lgkmcnt(4)
	v_mfma_f32_32x32x16_bf16 v[18:33], v[204:207], v[78:81], v[18:33]
	s_waitcnt vmcnt(1)
	ds_write_b128 v250, v[126:129] offset:25600
	s_waitcnt lgkmcnt(4)
	v_mfma_f32_32x32x16_bf16 v[2:17], v[208:211], v[78:81], v[2:17]
	s_waitcnt vmcnt(0)
	ds_write_b128 v250, v[150:153] offset:34816
	s_setprio 0
	s_branch .LBB0_1490
